# final sample-row phase: g_final loads issued with the partial loads instead of one at a time behind store-ack waits
# baseline (speedup 1.0000x reference)
.LBB0_731:
	s_or_b64 exec, exec, s[4:5]
	s_waitcnt lgkmcnt(0)
	s_barrier
	ds_read_b64 v[20:21], v73
	v_add_u32_e32 v28, 0x2400, v75
	v_ashrrev_i32_e32 v29, 31, v28
	s_addk_i32 s6, 0x400
	v_add_u32_e32 v72, 0x40000, v72
	s_waitcnt lgkmcnt(0)
	v_add_f32_e32 v8, v20, v21
	v_fmamk_f32 v8, v8, 0x3a000000, v74
	v_mul_f32_e32 v20, 0x4b800000, v8
	v_cmp_gt_f32_e32 vcc, s8, v8
	s_cmp_lt_i32 s6, 0
	v_lshl_add_u64 v[16:17], v[16:17], 0, s[2:3]
	v_cndmask_b32_e32 v8, v8, v20, vcc
	v_rsq_f32_e32 v8, v8
	v_lshlrev_b64 v[20:21], 13, v[28:29]
	v_lshl_add_u64 v[28:29], v[14:15], 0, v[20:21]
	v_mul_f32_e32 v20, 0x45800000, v8
	v_cndmask_b32_e32 v8, v8, v20, vcc
	v_pk_mul_f32 v[22:23], v[8:9], v[22:23] op_sel_hi:[0,1]
	v_pk_mul_f32 v[18:19], v[8:9], v[18:19] op_sel_hi:[0,1]
	v_pk_mul_f32 v[20:21], v[18:19], v[110:111]
	v_pk_mul_f32 v[18:19], v[22:23], v[108:109]
	global_store_dwordx4 v[28:29], v[18:21], off nt
	v_pk_mul_f32 v[22:23], v[8:9], v[4:5] op_sel_hi:[0,1]
	v_pk_mul_f32 v[4:5], v[8:9], v[6:7] op_sel_hi:[0,1]
	v_pk_mul_f32 v[4:5], v[4:5], v[112:113]
	v_pk_mul_f32 v[6:7], v[22:23], v[114:115]
	global_store_dwordx4 v[28:29], v[4:7], off offset:1024 nt
	v_pk_mul_f32 v[18:19], v[8:9], v[36:37] op_sel_hi:[0,1]
	v_pk_mul_f32 v[20:21], v[8:9], v[38:39] op_sel_hi:[0,1]
	v_pk_mul_f32 v[4:5], v[20:21], v[116:117]
	v_pk_mul_f32 v[6:7], v[18:19], v[118:119]
	global_store_dwordx4 v[28:29], v[4:7], off offset:2048 nt
	v_pk_mul_f32 v[18:19], v[8:9], v[0:1] op_sel_hi:[0,1]
	v_pk_mul_f32 v[0:1], v[8:9], v[2:3] op_sel_hi:[0,1]
	v_pk_mul_f32 v[0:1], v[0:1], v[120:121]
	v_pk_mul_f32 v[2:3], v[18:19], v[122:123]
	global_store_dwordx4 v[28:29], v[0:3], off offset:3072 nt
	s_barrier
	s_cbranch_scc0 .LBB0_734
.LBB0_732:
	global_load_dwordx4 v[108:111], v[12:13], off
	global_load_dwordx4 v[112:115], v[12:13], off offset:1024
	global_load_dwordx4 v[116:119], v[12:13], off offset:2048
	global_load_dwordx4 v[120:123], v[12:13], off offset:3072
	v_add_u32_e32 v75, s6, v148
	v_add_u32_e32 v0, 0x400, v75
	v_ashrrev_i32_e32 v0, 5, v0
	v_and_or_b32 v18, v0, -8, v66
	v_and_b32_e32 v0, 0xff00, v72
	v_lshlrev_b32_e32 v8, 1, v0
	v_ashrrev_i32_e32 v19, 31, v18
	v_lshl_add_u64 v[20:21], v[10:11], 0, v[8:9]
	v_lshlrev_b64 v[0:1], 17, v[18:19]
	v_lshl_add_u64 v[0:1], v[20:21], 0, v[0:1]
	v_add_co_u32_e32 v2, vcc, s7, v0
	s_nop 1
	v_addc_co_u32_e32 v3, vcc, 0, v1, vcc
	v_add_co_u32_e32 v4, vcc, s8, v0
	s_nop 1
	v_addc_co_u32_e32 v5, vcc, 0, v1, vcc
	v_add_co_u32_e32 v6, vcc, s9, v0
	s_nop 1
	v_addc_co_u32_e32 v7, vcc, 0, v1, vcc
	global_load_dwordx2 v[22:23], v[0:1], off
	global_load_dwordx2 v[84:85], v[2:3], off
	global_load_dwordx2 v[86:87], v[4:5], off
	global_load_dwordx2 v[88:89], v[6:7], off
	v_add_co_u32_e32 v2, vcc, s10, v0
	s_nop 1
	v_addc_co_u32_e32 v3, vcc, 0, v1, vcc
	v_add_co_u32_e32 v24, vcc, s11, v0
	s_nop 1
	v_addc_co_u32_e32 v25, vcc, 0, v1, vcc
	v_add_co_u32_e32 v26, vcc, s12, v0
	s_nop 1
	v_addc_co_u32_e32 v27, vcc, 0, v1, vcc
	v_add_co_u32_e32 v0, vcc, s13, v0
	s_nop 1
	v_addc_co_u32_e32 v1, vcc, 0, v1, vcc
	global_load_dwordx2 v[90:91], v[2:3], off
	global_load_dwordx2 v[92:93], v[24:25], off
	global_load_dwordx2 v[94:95], v[26:27], off
	global_load_dwordx2 v[96:97], v[0:1], off
	global_load_dwordx4 v[76:79], v[16:17], off offset:-3072 nt
	global_load_dwordx4 v[4:7], v[16:17], off offset:-2048 nt
	v_or_b32_e32 v0, 1, v18
	v_ashrrev_i32_e32 v1, 31, v0
	v_lshlrev_b64 v[0:1], 17, v[0:1]
	v_lshl_add_u64 v[0:1], v[20:21], 0, v[0:1]
	v_add_co_u32_e32 v2, vcc, s7, v0
	s_nop 1
	v_addc_co_u32_e32 v3, vcc, 0, v1, vcc
	v_add_co_u32_e32 v24, vcc, s8, v0
	s_nop 1
	v_addc_co_u32_e32 v25, vcc, 0, v1, vcc
	v_add_co_u32_e32 v26, vcc, s9, v0
	s_nop 1
	v_addc_co_u32_e32 v27, vcc, 0, v1, vcc
	global_load_dwordx2 v[98:99], v[0:1], off
	global_load_dwordx2 v[100:101], v[2:3], off
	global_load_dwordx2 v[62:63], v[24:25], off
	global_load_dwordx2 v[58:59], v[26:27], off
	v_add_co_u32_e32 v2, vcc, s10, v0
	s_nop 1
	v_addc_co_u32_e32 v3, vcc, 0, v1, vcc
	v_add_co_u32_e32 v24, vcc, s11, v0
	s_nop 1
	v_addc_co_u32_e32 v25, vcc, 0, v1, vcc
	v_add_co_u32_e32 v26, vcc, s12, v0
	s_nop 1
	v_addc_co_u32_e32 v27, vcc, 0, v1, vcc
	v_add_co_u32_e32 v0, vcc, s13, v0
	s_nop 1
	v_addc_co_u32_e32 v1, vcc, 0, v1, vcc
	global_load_dwordx2 v[64:65], v[2:3], off
	global_load_dwordx2 v[60:61], v[24:25], off
	global_load_dwordx2 v[54:55], v[26:27], off
	global_load_dwordx2 v[52:53], v[0:1], off
	v_or_b32_e32 v0, 2, v18
	v_ashrrev_i32_e32 v1, 31, v0
	v_lshlrev_b64 v[0:1], 17, v[0:1]
	v_lshl_add_u64 v[0:1], v[20:21], 0, v[0:1]
	v_add_co_u32_e32 v2, vcc, s7, v0
	v_or_b32_e32 v18, 3, v18
	s_nop 0
	v_addc_co_u32_e32 v3, vcc, 0, v1, vcc
	v_add_co_u32_e32 v24, vcc, s8, v0
	v_ashrrev_i32_e32 v19, 31, v18
	s_nop 0
	v_addc_co_u32_e32 v25, vcc, 0, v1, vcc
	v_add_co_u32_e32 v26, vcc, s9, v0
	v_lshlrev_b64 v[18:19], 17, v[18:19]
	s_nop 0
	v_addc_co_u32_e32 v27, vcc, 0, v1, vcc
	global_load_dwordx2 v[56:57], v[0:1], off
	global_load_dwordx2 v[50:51], v[2:3], off
	global_load_dwordx2 v[46:47], v[24:25], off
	global_load_dwordx2 v[42:43], v[26:27], off
	v_add_co_u32_e32 v24, vcc, s10, v0
	v_lshl_add_u64 v[18:19], v[20:21], 0, v[18:19]
	s_nop 0
	v_addc_co_u32_e32 v25, vcc, 0, v1, vcc
	v_add_co_u32_e32 v26, vcc, s11, v0
	s_nop 1
	v_addc_co_u32_e32 v27, vcc, 0, v1, vcc
	v_add_co_u32_e32 v28, vcc, s12, v0
	s_nop 1
	v_addc_co_u32_e32 v29, vcc, 0, v1, vcc
	v_add_co_u32_e32 v30, vcc, s13, v0
	s_nop 1
	v_addc_co_u32_e32 v31, vcc, 0, v1, vcc
	global_load_dwordx2 v[48:49], v[24:25], off
	global_load_dwordx2 v[44:45], v[26:27], off
	global_load_dwordx2 v[38:39], v[28:29], off
	global_load_dwordx2 v[36:37], v[30:31], off
	global_load_dwordx4 v[80:83], v[16:17], off offset:-1024 nt
	global_load_dwordx4 v[0:3], v[16:17], off nt
	v_add_co_u32_e32 v20, vcc, s7, v18
	s_nop 1
	v_addc_co_u32_e32 v21, vcc, 0, v19, vcc
	v_add_co_u32_e32 v24, vcc, s8, v18
	s_nop 1
	v_addc_co_u32_e32 v25, vcc, 0, v19, vcc
	v_add_co_u32_e32 v28, vcc, s9, v18
	s_nop 1
	v_addc_co_u32_e32 v29, vcc, 0, v19, vcc
	v_add_co_u32_e32 v102, vcc, s10, v18
	global_load_dwordx2 v[40:41], v[18:19], off
	global_load_dwordx2 v[34:35], v[20:21], off
	global_load_dwordx2 v[30:31], v[24:25], off
	global_load_dwordx2 v[26:27], v[28:29], off
	v_addc_co_u32_e32 v103, vcc, 0, v19, vcc
	v_add_co_u32_e32 v104, vcc, s11, v18
	s_nop 1
	v_addc_co_u32_e32 v105, vcc, 0, v19, vcc
	v_add_co_u32_e32 v106, vcc, s12, v18
	s_nop 1
	v_addc_co_u32_e32 v107, vcc, 0, v19, vcc
	v_add_co_u32_e32 v18, vcc, s13, v18
	s_nop 1
	v_addc_co_u32_e32 v19, vcc, 0, v19, vcc
	global_load_dwordx2 v[32:33], v[102:103], off
	global_load_dwordx2 v[28:29], v[104:105], off
	global_load_dwordx2 v[24:25], v[106:107], off
	global_load_dwordx2 v[20:21], v[18:19], off
	s_waitcnt vmcnt(35)
	v_lshlrev_b32_e32 v18, 16, v22
	v_and_b32_e32 v19, 0xffff0000, v22
	v_lshlrev_b32_e32 v22, 16, v23
	v_and_b32_e32 v23, 0xffff0000, v23
	s_waitcnt vmcnt(27)
	v_pk_add_f32 v[18:19], v[76:77], v[18:19]
	v_pk_add_f32 v[22:23], v[78:79], v[22:23]
	v_lshlrev_b32_e32 v76, 16, v84
	v_and_b32_e32 v77, 0xffff0000, v84
	v_lshlrev_b32_e32 v78, 16, v85
	v_and_b32_e32 v79, 0xffff0000, v85
	v_pk_add_f32 v[22:23], v[22:23], v[78:79]
	v_pk_add_f32 v[18:19], v[18:19], v[76:77]
	v_lshlrev_b32_e32 v76, 16, v86
	v_and_b32_e32 v77, 0xffff0000, v86
	v_lshlrev_b32_e32 v78, 16, v87
	v_and_b32_e32 v79, 0xffff0000, v87
	v_pk_add_f32 v[18:19], v[18:19], v[76:77]
	v_pk_add_f32 v[22:23], v[22:23], v[78:79]
	v_lshlrev_b32_e32 v76, 16, v88
	v_and_b32_e32 v77, 0xffff0000, v88
	v_lshlrev_b32_e32 v78, 16, v89
	v_and_b32_e32 v79, 0xffff0000, v89
	v_pk_add_f32 v[22:23], v[22:23], v[78:79]
	v_pk_add_f32 v[18:19], v[18:19], v[76:77]
	v_lshlrev_b32_e32 v76, 16, v90
	v_and_b32_e32 v77, 0xffff0000, v90
	v_lshlrev_b32_e32 v78, 16, v91
	v_and_b32_e32 v79, 0xffff0000, v91
	v_pk_add_f32 v[18:19], v[18:19], v[76:77]
	v_pk_add_f32 v[22:23], v[22:23], v[78:79]
	v_lshlrev_b32_e32 v76, 16, v92
	v_and_b32_e32 v77, 0xffff0000, v92
	v_lshlrev_b32_e32 v78, 16, v93
	v_and_b32_e32 v79, 0xffff0000, v93
	v_pk_add_f32 v[22:23], v[22:23], v[78:79]
	v_pk_add_f32 v[18:19], v[18:19], v[76:77]
	v_lshlrev_b32_e32 v76, 16, v94
	v_and_b32_e32 v77, 0xffff0000, v94
	v_lshlrev_b32_e32 v78, 16, v95
	v_and_b32_e32 v79, 0xffff0000, v95
	v_pk_add_f32 v[76:77], v[18:19], v[76:77]
	v_pk_add_f32 v[18:19], v[22:23], v[78:79]
	v_lshlrev_b32_e32 v22, 16, v96
	v_and_b32_e32 v23, 0xffff0000, v96
	v_lshlrev_b32_e32 v78, 16, v97
	v_and_b32_e32 v79, 0xffff0000, v97
	v_pk_add_f32 v[18:19], v[18:19], v[78:79]
	v_pk_add_f32 v[22:23], v[76:77], v[22:23]
	v_mul_f32_e32 v76, v19, v19
	v_mul_f32_e32 v8, v23, v23
	v_fmac_f32_e32 v8, v22, v22
	v_fmac_f32_e32 v76, v18, v18
	v_add_f32_e32 v8, v8, v76
	s_waitcnt vmcnt(25)
	v_lshlrev_b32_e32 v76, 16, v98
	v_and_b32_e32 v77, 0xffff0000, v98
	v_lshlrev_b32_e32 v78, 16, v99
	v_and_b32_e32 v79, 0xffff0000, v99
	v_pk_add_f32 v[4:5], v[4:5], v[76:77]
	v_pk_add_f32 v[6:7], v[6:7], v[78:79]
	s_waitcnt vmcnt(24)
	v_lshlrev_b32_e32 v76, 16, v100
	v_and_b32_e32 v77, 0xffff0000, v100
	v_lshlrev_b32_e32 v78, 16, v101
	v_and_b32_e32 v79, 0xffff0000, v101
	v_pk_add_f32 v[6:7], v[6:7], v[78:79]
	v_pk_add_f32 v[4:5], v[4:5], v[76:77]
	s_waitcnt vmcnt(23)
	v_lshlrev_b32_e32 v76, 16, v62
	v_and_b32_e32 v77, 0xffff0000, v62
	v_lshlrev_b32_e32 v62, 16, v63
	v_and_b32_e32 v63, 0xffff0000, v63
	v_pk_add_f32 v[4:5], v[4:5], v[76:77]
	v_pk_add_f32 v[6:7], v[6:7], v[62:63]
	s_waitcnt vmcnt(22)
	v_lshlrev_b32_e32 v62, 16, v58
	v_and_b32_e32 v63, 0xffff0000, v58
	v_lshlrev_b32_e32 v58, 16, v59
	v_and_b32_e32 v59, 0xffff0000, v59
	v_pk_add_f32 v[6:7], v[6:7], v[58:59]
	v_pk_add_f32 v[4:5], v[4:5], v[62:63]
	s_waitcnt vmcnt(21)
	v_lshlrev_b32_e32 v58, 16, v64
	v_and_b32_e32 v59, 0xffff0000, v64
	v_lshlrev_b32_e32 v62, 16, v65
	v_and_b32_e32 v63, 0xffff0000, v65
	v_pk_add_f32 v[4:5], v[4:5], v[58:59]
	v_pk_add_f32 v[6:7], v[6:7], v[62:63]
	s_waitcnt vmcnt(20)
	v_lshlrev_b32_e32 v58, 16, v60
	v_and_b32_e32 v59, 0xffff0000, v60
	v_lshlrev_b32_e32 v60, 16, v61
	v_and_b32_e32 v61, 0xffff0000, v61
	v_pk_add_f32 v[6:7], v[6:7], v[60:61]
	v_pk_add_f32 v[4:5], v[4:5], v[58:59]
	s_waitcnt vmcnt(19)
	v_lshlrev_b32_e32 v58, 16, v54
	v_and_b32_e32 v59, 0xffff0000, v54
	v_lshlrev_b32_e32 v54, 16, v55
	v_and_b32_e32 v55, 0xffff0000, v55
	v_pk_add_f32 v[58:59], v[4:5], v[58:59]
	v_pk_add_f32 v[4:5], v[6:7], v[54:55]
	s_waitcnt vmcnt(18)
	v_lshlrev_b32_e32 v6, 16, v52
	v_and_b32_e32 v7, 0xffff0000, v52
	v_lshlrev_b32_e32 v52, 16, v53
	v_and_b32_e32 v53, 0xffff0000, v53
	v_pk_add_f32 v[4:5], v[4:5], v[52:53]
	v_pk_add_f32 v[6:7], v[58:59], v[6:7]
	v_mul_f32_e32 v53, v5, v5
	v_mul_f32_e32 v52, v7, v7
	v_fmac_f32_e32 v52, v6, v6
	v_fmac_f32_e32 v53, v4, v4
	v_add_f32_e32 v52, v52, v53
	v_add_f32_e32 v8, v8, v52
	s_waitcnt vmcnt(17)
	v_lshlrev_b32_e32 v52, 16, v56
	v_and_b32_e32 v53, 0xffff0000, v56
	v_lshlrev_b32_e32 v54, 16, v57
	v_and_b32_e32 v55, 0xffff0000, v57
	s_waitcnt vmcnt(9)
	v_pk_add_f32 v[52:53], v[80:81], v[52:53]
	v_pk_add_f32 v[54:55], v[82:83], v[54:55]
	v_lshlrev_b32_e32 v56, 16, v50
	v_and_b32_e32 v57, 0xffff0000, v50
	v_lshlrev_b32_e32 v50, 16, v51
	v_and_b32_e32 v51, 0xffff0000, v51
	v_pk_add_f32 v[50:51], v[54:55], v[50:51]
	v_pk_add_f32 v[52:53], v[52:53], v[56:57]
	v_lshlrev_b32_e32 v54, 16, v46
	v_and_b32_e32 v55, 0xffff0000, v46
	v_lshlrev_b32_e32 v46, 16, v47
	v_and_b32_e32 v47, 0xffff0000, v47
	v_pk_add_f32 v[52:53], v[52:53], v[54:55]
	v_pk_add_f32 v[46:47], v[50:51], v[46:47]
	v_lshlrev_b32_e32 v50, 16, v42
	v_and_b32_e32 v51, 0xffff0000, v42
	v_lshlrev_b32_e32 v42, 16, v43
	v_and_b32_e32 v43, 0xffff0000, v43
	v_pk_add_f32 v[42:43], v[46:47], v[42:43]
	v_pk_add_f32 v[46:47], v[52:53], v[50:51]
	v_lshlrev_b32_e32 v50, 16, v48
	v_and_b32_e32 v51, 0xffff0000, v48
	v_lshlrev_b32_e32 v48, 16, v49
	v_and_b32_e32 v49, 0xffff0000, v49
	v_pk_add_f32 v[46:47], v[46:47], v[50:51]
	v_pk_add_f32 v[42:43], v[42:43], v[48:49]
	v_lshlrev_b32_e32 v48, 16, v44
	v_and_b32_e32 v49, 0xffff0000, v44
	v_lshlrev_b32_e32 v44, 16, v45
	v_and_b32_e32 v45, 0xffff0000, v45
	v_pk_add_f32 v[42:43], v[42:43], v[44:45]
	v_pk_add_f32 v[44:45], v[46:47], v[48:49]
	v_lshlrev_b32_e32 v46, 16, v38
	v_and_b32_e32 v47, 0xffff0000, v38
	v_lshlrev_b32_e32 v38, 16, v39
	v_and_b32_e32 v39, 0xffff0000, v39
	v_pk_add_f32 v[44:45], v[44:45], v[46:47]
	v_pk_add_f32 v[38:39], v[42:43], v[38:39]
	v_lshlrev_b32_e32 v42, 16, v36
	v_and_b32_e32 v43, 0xffff0000, v36
	v_lshlrev_b32_e32 v36, 16, v37
	v_and_b32_e32 v37, 0xffff0000, v37
	v_pk_add_f32 v[36:37], v[38:39], v[36:37]
	v_pk_add_f32 v[38:39], v[44:45], v[42:43]
	v_mul_f32_e32 v43, v37, v37
	v_mul_f32_e32 v42, v39, v39
	v_fmac_f32_e32 v42, v38, v38
	v_fmac_f32_e32 v43, v36, v36
	v_add_f32_e32 v42, v42, v43
	v_add_f32_e32 v8, v8, v42
	s_waitcnt vmcnt(7)
	v_lshlrev_b32_e32 v42, 16, v40
	v_and_b32_e32 v43, 0xffff0000, v40
	v_lshlrev_b32_e32 v40, 16, v41
	v_and_b32_e32 v41, 0xffff0000, v41
	v_pk_add_f32 v[0:1], v[0:1], v[42:43]
	v_pk_add_f32 v[2:3], v[2:3], v[40:41]
	s_waitcnt vmcnt(6)
	v_lshlrev_b32_e32 v40, 16, v34
	v_and_b32_e32 v41, 0xffff0000, v34
	v_lshlrev_b32_e32 v34, 16, v35
	v_and_b32_e32 v35, 0xffff0000, v35
	v_pk_add_f32 v[2:3], v[2:3], v[34:35]
	v_pk_add_f32 v[0:1], v[0:1], v[40:41]
	s_waitcnt vmcnt(5)
	v_lshlrev_b32_e32 v34, 16, v30
	v_and_b32_e32 v35, 0xffff0000, v30
	v_lshlrev_b32_e32 v30, 16, v31
	v_and_b32_e32 v31, 0xffff0000, v31
	v_pk_add_f32 v[0:1], v[0:1], v[34:35]
	v_pk_add_f32 v[2:3], v[2:3], v[30:31]
	s_waitcnt vmcnt(4)
	v_lshlrev_b32_e32 v30, 16, v26
	v_and_b32_e32 v31, 0xffff0000, v26
	v_lshlrev_b32_e32 v26, 16, v27
	v_and_b32_e32 v27, 0xffff0000, v27
	v_pk_add_f32 v[2:3], v[2:3], v[26:27]
	v_pk_add_f32 v[0:1], v[0:1], v[30:31]
	s_waitcnt vmcnt(3)
	v_lshlrev_b32_e32 v26, 16, v32
	v_and_b32_e32 v27, 0xffff0000, v32
	v_lshlrev_b32_e32 v30, 16, v33
	v_and_b32_e32 v31, 0xffff0000, v33
	v_pk_add_f32 v[0:1], v[0:1], v[26:27]
	v_pk_add_f32 v[2:3], v[2:3], v[30:31]
	s_waitcnt vmcnt(2)
	v_lshlrev_b32_e32 v26, 16, v28
	v_and_b32_e32 v27, 0xffff0000, v28
	v_lshlrev_b32_e32 v28, 16, v29
	v_and_b32_e32 v29, 0xffff0000, v29
	v_pk_add_f32 v[2:3], v[2:3], v[28:29]
	v_pk_add_f32 v[0:1], v[0:1], v[26:27]
	s_waitcnt vmcnt(1)
	v_lshlrev_b32_e32 v26, 16, v24
	v_and_b32_e32 v27, 0xffff0000, v24
	v_lshlrev_b32_e32 v24, 16, v25
	v_and_b32_e32 v25, 0xffff0000, v25
	v_pk_add_f32 v[26:27], v[0:1], v[26:27]
	v_pk_add_f32 v[0:1], v[2:3], v[24:25]
	s_waitcnt vmcnt(0)
	v_lshlrev_b32_e32 v2, 16, v20
	v_and_b32_e32 v3, 0xffff0000, v20
	v_lshlrev_b32_e32 v20, 16, v21
	v_and_b32_e32 v21, 0xffff0000, v21
	v_pk_add_f32 v[0:1], v[0:1], v[20:21]
	v_pk_add_f32 v[2:3], v[26:27], v[2:3]
	v_mul_f32_e32 v21, v1, v1
	v_mul_f32_e32 v20, v3, v3
	v_fmac_f32_e32 v20, v2, v2
	v_fmac_f32_e32 v21, v0, v0
	v_add_f32_e32 v20, v20, v21
	v_add_f32_e32 v8, v8, v20
	ds_bpermute_b32 v20, v150, v8
	s_waitcnt lgkmcnt(0)
	v_add_f32_e32 v8, v8, v20
	ds_bpermute_b32 v20, v149, v8
	s_waitcnt lgkmcnt(0)
	v_add_f32_e32 v8, v8, v20
	ds_bpermute_b32 v20, v67, v8
	s_waitcnt lgkmcnt(0)
	v_add_f32_e32 v8, v8, v20
	ds_bpermute_b32 v20, v68, v8
	s_waitcnt lgkmcnt(0)
	v_add_f32_e32 v8, v8, v20
	ds_bpermute_b32 v20, v69, v8
	s_waitcnt lgkmcnt(0)
	v_add_f32_e32 v8, v8, v20
	ds_bpermute_b32 v20, v70, v8
	s_and_saveexec_b64 s[4:5], s[0:1]
	s_cbranch_execz .LBB0_731
	s_waitcnt lgkmcnt(0)
	v_add_f32_e32 v8, v8, v20
	ds_write_b32 v71, v8
	s_branch .LBB0_731
